# SB key-loop countdown on the scalar unit (s_sub_u32 + s_cselect_b64) instead of v_sub_co + v_readfirstlane; on top of flag-address hoist
# baseline (speedup 1.0000x reference)
.LBB0_355:
	s_sub_u32 s88, s88, 1
	s_cselect_b64 s[84:85], exec, 0
	s_or_b64 s[82:83], s[82:83], s[84:85]
	s_addk_i32 s89, 0x4000
	s_andn2_b64 vcc, exec, s[82:83]
	s_add_i32 s86, s86, 8
	s_cbranch_vccz .LBB0_377

.LBB0_377:
	v_mov_b32_e32 v82, s88
	s_mov_b32 s36, -2.0
	s_mov_b32 s38, 0xc2000000
	s_mov_b32 s40, 0xc2080000
	s_mov_b32 s42, 0xc1000000
	s_mov_b32 s44, 0xc2200000
	s_mov_b32 s46, 0xc1200000
	s_mov_b32 s48, 0xc2280000
	s_mov_b32 s50, 0xc1800000
	s_mov_b32 s52, 0xc2400000
	s_mov_b32 s54, 0xc1900000
	s_mov_b32 s58, 0xc2480000
	s_mov_b32 s60, 0xc1c00000
	s_mov_b32 s62, 0xc2600000
	s_mov_b32 s64, 0xc1d00000
	s_mov_b32 s66, 0xc2680000
	v_readlane_b32 s84, v255, 51
	s_andn2_b64 vcc, exec, s[72:73]
	s_mov_b32 s37, 0xc0400000
	s_mov_b32 s39, 0xc2040000
	s_mov_b32 s41, 0xc20c0000
	s_mov_b32 s43, 0xc1100000
	s_mov_b32 s45, 0xc2240000
	s_mov_b32 s47, 0xc1300000
	s_mov_b32 s49, 0xc22c0000
	s_mov_b32 s51, 0xc1880000
	s_mov_b32 s53, 0xc2440000
	s_mov_b32 s55, 0xc1980000
	s_mov_b32 s59, 0xc24c0000
	s_mov_b32 s61, 0xc1c80000
	s_mov_b32 s63, 0xc2640000
	s_mov_b32 s65, 0xc1d80000
	s_mov_b32 s67, 0xc26c0000
	v_readlane_b32 s35, v255, 43
	v_readlane_b32 s69, v255, 44
	s_mov_b32 s82, 0xff800000
	s_mov_b32 s83, 0x3e38aa3b
	v_readlane_b32 s85, v255, 52
	s_cbranch_vccnz .LBB0_379
	v_mfma_f32_32x32x16_bf16 v[18:33], v[34:37], v[66:69], v[18:33]
	s_waitcnt lgkmcnt(10)
	v_mfma_f32_32x32x16_bf16 v[2:17], v[38:41], v[66:69], v[2:17]
	v_mfma_f32_32x32x16_bf16 v[18:33], v[42:45], v[70:73], v[18:33]
	s_waitcnt lgkmcnt(8)
	v_mfma_f32_32x32x16_bf16 v[2:17], v[46:49], v[70:73], v[2:17]
	s_waitcnt lgkmcnt(6)
	v_mfma_f32_32x32x16_bf16 v[18:33], v[50:53], v[74:77], v[18:33]
	s_waitcnt lgkmcnt(2)
	v_mfma_f32_32x32x16_bf16 v[2:17], v[54:57], v[74:77], v[2:17]
	v_mfma_f32_32x32x16_bf16 v[18:33], v[58:61], v[78:81], v[18:33]
	s_waitcnt lgkmcnt(0)
	v_mfma_f32_32x32x16_bf16 v[2:17], v[62:65], v[78:81], v[2:17]
